# v20 + out-proj epilogue rewritten by hand as two passes (all residual loads then all stores, no store acks inside the load wait chain)
# baseline (speedup 1.0000x reference)
;     __device__ __forceinline__ void operator()(const f32x4 (&acc)[2][2][4][2], const Unit& u, int wr, int wc, int fr, int fq) const {
;     ...
;         f32x4 nx[4];
;         { int r_ = row0; asm volatile("" : "+v"(r_)); const float* rs = rsrc(r_) + col0; nx[0] = *(const f32x4*)(rs); nx[1] = *(const f32x4*)(rs + 4); nx[2] = *(const f32x4*)(rs + 128); nx[3] = *(const f32x4*)(rs + 132); }
; #pragma unroll
;         for (int ai = 0; ai < 2; ++ai)
; #pragma unroll
;             for (int m = 0; m < 4; ++m) {
;                 int row_ = row0 + ai * 128 + m * 16; asm volatile("" : "+v"(row_)); const int row = row_;
;                 f32x4 cu[4] = {nx[0], nx[1], nx[2], nx[3]};
;                 if (ai * 4 + m < 7) { const int it = ai * 4 + m + 1; int r_ = row0 + (it >> 2) * 128 + (it & 3) * 16; asm volatile("" : "+v"(r_)); const float* rs = rsrc(r_) + col0;
;                     nx[0] = *(const f32x4*)(rs); nx[1] = *(const f32x4*)(rs + 4); nx[2] = *(const f32x4*)(rs + 128); nx[3] = *(const f32x4*)(rs + 132); }
;                 float* rd = row < MR ? out_real + (size_t)row * 1024 : XM + (size_t)(row - MR) * 1024;
;                 float s = 0.f;
; #pragma unroll
;                 for (int bj = 0; bj < 2; ++bj) {
;                     const int col = col0 + bj * 128;
;                     const f32x4 x0 = cu[2 * bj] + acc[ai][bj][m][0], x1 = cu[2 * bj + 1] + acc[ai][bj][m][1];
.LBB0_988:
	s_lshl_b32 s4, s4, 8
	s_add_i32 s4, s4, s67
	v_mbcnt_lo_u32_b32 v179, -1, 0
	v_mbcnt_hi_u32_b32 v179, -1, v179
	v_readlane_b32 s25, v255, 22
	v_and_or_b32 v185, v179, 15, s4
	s_lshl_b32 s4, s30, 8
	v_ashrrev_i32_e32 v18, 1, v179
	s_or_b32 s4, s4, s68
	v_and_b32_e32 v18, -8, v18
	v_add_u32_e32 v176, s4, v18
	v_mov_b32_e32 v18, v185
	v_ashrrev_i32_e32 v177, 31, v176
	v_readlane_b32 s34, v255, 27
	v_readlane_b32 s35, v255, 28
	s_movk_i32 s23, 0x7fff
	s_lshl_b32 s30, s30, 2
	s_ashr_i32 s31, s30, 31
	s_lshl_b32 s48, s62, 2
	v_cmp_gt_u32_e64 s[4:5], 16, v179
	v_mov_b32_e32 v182, s56
	v_mov_b32_e32 v183, s57
	v_mov_b32_e32 v186, s58
	v_mov_b32_e32 v187, s59
	v_mov_b32_e32 v18, v185
	v_add_u32_e32 v180, 0x7fff8000, v18
	v_and_b32_e32 v180, s25, v180
	v_ashrrev_i32_e32 v181, 31, v18
	v_cmp_gt_i32_e32 vcc, s92, v18
	s_nop 1
	v_cndmask_b32_e32 v180, v180, v18, vcc
	v_cndmask_b32_e32 v181, 0, v181, vcc
	v_cndmask_b32_e32 v178, v187, v183, vcc
	v_cndmask_b32_e32 v179, v186, v182, vcc
	v_lshlrev_b64 v[180:181], 12, v[180:181]
	v_lshl_add_u64 v[180:181], v[178:179], 0, v[180:181]
	v_lshl_add_u64 v[180:181], v[176:177], 2, v[180:181]
	global_load_dwordx4 v[148:151], v[180:181], off
	global_load_dwordx4 v[152:155], v[180:181], off offset:16
	global_load_dwordx4 v[156:159], v[180:181], off offset:512
	global_load_dwordx4 v[160:163], v[180:181], off offset:528
	v_add_u32_e32 v18, 16, v185
	v_add_u32_e32 v180, 0x7fff8000, v18
	v_and_b32_e32 v180, s25, v180
	v_ashrrev_i32_e32 v181, 31, v18
	v_cmp_gt_i32_e32 vcc, s92, v18
	s_nop 1
	v_cndmask_b32_e32 v180, v180, v18, vcc
	v_cndmask_b32_e32 v181, 0, v181, vcc
	v_cndmask_b32_e32 v178, v187, v183, vcc
	v_cndmask_b32_e32 v179, v186, v182, vcc
	v_lshlrev_b64 v[180:181], 12, v[180:181]
	v_lshl_add_u64 v[180:181], v[178:179], 0, v[180:181]
	v_lshl_add_u64 v[180:181], v[176:177], 2, v[180:181]
	global_load_dwordx4 v[132:135], v[180:181], off
	global_load_dwordx4 v[136:139], v[180:181], off offset:16
	global_load_dwordx4 v[140:143], v[180:181], off offset:512
	global_load_dwordx4 v[144:147], v[180:181], off offset:528
	s_waitcnt vmcnt(4)
	v_pk_add_f32 v[128:129], v[128:129], v[148:149]
	v_pk_add_f32 v[130:131], v[130:131], v[150:151]
	v_pk_add_f32 v[124:125], v[124:125], v[152:153]
	v_pk_add_f32 v[126:127], v[126:127], v[154:155]
	v_pk_add_f32 v[120:121], v[120:121], v[156:157]
	v_pk_add_f32 v[122:123], v[122:123], v[158:159]
	v_pk_add_f32 v[116:117], v[116:117], v[160:161]
	v_pk_add_f32 v[118:119], v[118:119], v[162:163]
	v_add_u32_e32 v18, 32, v185
	v_add_u32_e32 v180, 0x7fff8000, v18
	v_and_b32_e32 v180, s25, v180
	v_ashrrev_i32_e32 v181, 31, v18
	v_cmp_gt_i32_e32 vcc, s92, v18
	s_nop 1
	v_cndmask_b32_e32 v180, v180, v18, vcc
	v_cndmask_b32_e32 v181, 0, v181, vcc
	v_cndmask_b32_e32 v178, v187, v183, vcc
	v_cndmask_b32_e32 v179, v186, v182, vcc
	v_lshlrev_b64 v[180:181], 12, v[180:181]
	v_lshl_add_u64 v[180:181], v[178:179], 0, v[180:181]
	v_lshl_add_u64 v[180:181], v[176:177], 2, v[180:181]
	global_load_dwordx4 v[148:151], v[180:181], off
	global_load_dwordx4 v[152:155], v[180:181], off offset:16
	global_load_dwordx4 v[156:159], v[180:181], off offset:512
	global_load_dwordx4 v[160:163], v[180:181], off offset:528
	s_waitcnt vmcnt(4)
	v_pk_add_f32 v[112:113], v[112:113], v[132:133]
	v_pk_add_f32 v[114:115], v[114:115], v[134:135]
	v_pk_add_f32 v[108:109], v[108:109], v[136:137]
	v_pk_add_f32 v[110:111], v[110:111], v[138:139]
	v_pk_add_f32 v[104:105], v[104:105], v[140:141]
	v_pk_add_f32 v[106:107], v[106:107], v[142:143]
	v_pk_add_f32 v[100:101], v[100:101], v[144:145]
	v_pk_add_f32 v[102:103], v[102:103], v[146:147]
	v_add_u32_e32 v18, 48, v185
	v_add_u32_e32 v180, 0x7fff8000, v18
	v_and_b32_e32 v180, s25, v180
	v_ashrrev_i32_e32 v181, 31, v18
	v_cmp_gt_i32_e32 vcc, s92, v18
	s_nop 1
	v_cndmask_b32_e32 v180, v180, v18, vcc
	v_cndmask_b32_e32 v181, 0, v181, vcc
	v_cndmask_b32_e32 v178, v187, v183, vcc
	v_cndmask_b32_e32 v179, v186, v182, vcc
	v_lshlrev_b64 v[180:181], 12, v[180:181]
	v_lshl_add_u64 v[180:181], v[178:179], 0, v[180:181]
	v_lshl_add_u64 v[180:181], v[176:177], 2, v[180:181]
	global_load_dwordx4 v[132:135], v[180:181], off
	global_load_dwordx4 v[136:139], v[180:181], off offset:16
	global_load_dwordx4 v[140:143], v[180:181], off offset:512
	global_load_dwordx4 v[144:147], v[180:181], off offset:528
	s_waitcnt vmcnt(4)
	v_pk_add_f32 v[96:97], v[96:97], v[148:149]
	v_pk_add_f32 v[98:99], v[98:99], v[150:151]
	v_pk_add_f32 v[92:93], v[92:93], v[152:153]
	v_pk_add_f32 v[94:95], v[94:95], v[154:155]
	v_pk_add_f32 v[88:89], v[88:89], v[156:157]
	v_pk_add_f32 v[90:91], v[90:91], v[158:159]
	v_pk_add_f32 v[84:85], v[84:85], v[160:161]
	v_pk_add_f32 v[86:87], v[86:87], v[162:163]
	v_add_u32_e32 v18, 128, v185
	v_add_u32_e32 v180, 0x7fff8000, v18
	v_and_b32_e32 v180, s25, v180
	v_ashrrev_i32_e32 v181, 31, v18
	v_cmp_gt_i32_e32 vcc, s92, v18
	s_nop 1
	v_cndmask_b32_e32 v180, v180, v18, vcc
	v_cndmask_b32_e32 v181, 0, v181, vcc
	v_cndmask_b32_e32 v178, v187, v183, vcc
	v_cndmask_b32_e32 v179, v186, v182, vcc
	v_lshlrev_b64 v[180:181], 12, v[180:181]
	v_lshl_add_u64 v[180:181], v[178:179], 0, v[180:181]
	v_lshl_add_u64 v[180:181], v[176:177], 2, v[180:181]
	global_load_dwordx4 v[148:151], v[180:181], off
	global_load_dwordx4 v[152:155], v[180:181], off offset:16
	global_load_dwordx4 v[156:159], v[180:181], off offset:512
	global_load_dwordx4 v[160:163], v[180:181], off offset:528
	s_waitcnt vmcnt(4)
; __device__ __forceinline__ u32x4 pack8(const f32x4& v0, const f32x4& v1) { u32x4 w; w.x = cvt_pk_bf16(v0[0], v0[1]); w.y = cvt_pk_bf16(v0[2], v0[3]); w.z = cvt_pk_bf16(v1[0], v1[1]); w.w = cvt_pk_bf16(v1[2], v1[3]); return w; }
; __device__ __forceinline__ float sumsq8(const f32x4& a, const f32x4& b) { return (a[0] * a[0] + a[1] * a[1]) + (a[2] * a[2] + a[3] * a[3]) + (b[0] * b[0] + b[1] * b[1]) + (b[2] * b[2] + b[3] * b[3]); }
;     __device__ __forceinline__ void operator()(const f32x4 (&acc)[2][2][4][2], const Unit& u, int wr, int wc, int fr, int fq) const {
;     ...
;                 int row_ = row0 + ai * 128 + m * 16; asm volatile("" : "+v"(row_)); const int row = row_;
;                 f32x4 cu[4] = {nx[0], nx[1], nx[2], nx[3]};
;                 if (ai * 4 + m < 7) { const int it = ai * 4 + m + 1; int r_ = row0 + (it >> 2) * 128 + (it & 3) * 16; asm volatile("" : "+v"(r_)); const float* rs = rsrc(r_) + col0;
;                     nx[0] = *(const f32x4*)(rs); nx[1] = *(const f32x4*)(rs + 4); nx[2] = *(const f32x4*)(rs + 128); nx[3] = *(const f32x4*)(rs + 132); }
;                 float* rd = row < MR ? out_real + (size_t)row * 1024 : XM + (size_t)(row - MR) * 1024;
;                 float s = 0.f;
; #pragma unroll
;                 for (int bj = 0; bj < 2; ++bj) {
;                     const int col = col0 + bj * 128;
;                     const f32x4 x0 = cu[2 * bj] + acc[ai][bj][m][0], x1 = cu[2 * bj + 1] + acc[ai][bj][m][1];
;                     *(f32x4*)(rd + col) = x0; *(f32x4*)(rd + col + 4) = x1;
;                     if (feed_next) { *(u32x4*)(XB + (size_t)row * 1024 + col) = pack8(x0, x1); s += sumsq8(x0, x1); }
;                 }
;                 if (feed_next) { s = quad_sum(s); if (fq == 0) SSQX[(size_t)row * 16 + u.pn * 4 + wc] = s; }
	v_pk_add_f32 v[80:81], v[80:81], v[132:133]
	v_pk_add_f32 v[82:83], v[82:83], v[134:135]
	v_pk_add_f32 v[76:77], v[76:77], v[136:137]
	v_pk_add_f32 v[78:79], v[78:79], v[138:139]
	v_pk_add_f32 v[72:73], v[72:73], v[140:141]
	v_pk_add_f32 v[74:75], v[74:75], v[142:143]
	v_pk_add_f32 v[68:69], v[68:69], v[144:145]
	v_pk_add_f32 v[70:71], v[70:71], v[146:147]
	v_add_u32_e32 v18, 144, v185
	v_add_u32_e32 v180, 0x7fff8000, v18
	v_and_b32_e32 v180, s25, v180
	v_ashrrev_i32_e32 v181, 31, v18
	v_cmp_gt_i32_e32 vcc, s92, v18
	s_nop 1
	v_cndmask_b32_e32 v180, v180, v18, vcc
	v_cndmask_b32_e32 v181, 0, v181, vcc
	v_cndmask_b32_e32 v178, v187, v183, vcc
	v_cndmask_b32_e32 v179, v186, v182, vcc
	v_lshlrev_b64 v[180:181], 12, v[180:181]
	v_lshl_add_u64 v[180:181], v[178:179], 0, v[180:181]
	v_lshl_add_u64 v[180:181], v[176:177], 2, v[180:181]
	global_load_dwordx4 v[132:135], v[180:181], off
	global_load_dwordx4 v[136:139], v[180:181], off offset:16
	global_load_dwordx4 v[140:143], v[180:181], off offset:512
	global_load_dwordx4 v[144:147], v[180:181], off offset:528
	s_waitcnt vmcnt(4)
	v_pk_add_f32 v[64:65], v[64:65], v[148:149]
	v_pk_add_f32 v[66:67], v[66:67], v[150:151]
	v_pk_add_f32 v[60:61], v[60:61], v[152:153]
	v_pk_add_f32 v[62:63], v[62:63], v[154:155]
	v_pk_add_f32 v[56:57], v[56:57], v[156:157]
	v_pk_add_f32 v[58:59], v[58:59], v[158:159]
	v_pk_add_f32 v[52:53], v[52:53], v[160:161]
	v_pk_add_f32 v[54:55], v[54:55], v[162:163]
	v_add_u32_e32 v18, 160, v185
	v_add_u32_e32 v180, 0x7fff8000, v18
	v_and_b32_e32 v180, s25, v180
	v_ashrrev_i32_e32 v181, 31, v18
	v_cmp_gt_i32_e32 vcc, s92, v18
	s_nop 1
	v_cndmask_b32_e32 v180, v180, v18, vcc
	v_cndmask_b32_e32 v181, 0, v181, vcc
	v_cndmask_b32_e32 v178, v187, v183, vcc
	v_cndmask_b32_e32 v179, v186, v182, vcc
	v_lshlrev_b64 v[180:181], 12, v[180:181]
	v_lshl_add_u64 v[180:181], v[178:179], 0, v[180:181]
	v_lshl_add_u64 v[180:181], v[176:177], 2, v[180:181]
	global_load_dwordx4 v[148:151], v[180:181], off
	global_load_dwordx4 v[152:155], v[180:181], off offset:16
	global_load_dwordx4 v[156:159], v[180:181], off offset:512
	global_load_dwordx4 v[160:163], v[180:181], off offset:528
	s_waitcnt vmcnt(4)
	v_pk_add_f32 v[48:49], v[48:49], v[132:133]
	v_pk_add_f32 v[50:51], v[50:51], v[134:135]
	v_pk_add_f32 v[44:45], v[44:45], v[136:137]
	v_pk_add_f32 v[46:47], v[46:47], v[138:139]
	v_pk_add_f32 v[40:41], v[40:41], v[140:141]
	v_pk_add_f32 v[42:43], v[42:43], v[142:143]
	v_pk_add_f32 v[36:37], v[36:37], v[144:145]
	v_pk_add_f32 v[38:39], v[38:39], v[146:147]
	v_add_u32_e32 v18, 176, v185
	v_add_u32_e32 v180, 0x7fff8000, v18
	v_and_b32_e32 v180, s25, v180
	v_ashrrev_i32_e32 v181, 31, v18
	v_cmp_gt_i32_e32 vcc, s92, v18
	s_nop 1
	v_cndmask_b32_e32 v180, v180, v18, vcc
	v_cndmask_b32_e32 v181, 0, v181, vcc
	v_cndmask_b32_e32 v178, v187, v183, vcc
	v_cndmask_b32_e32 v179, v186, v182, vcc
	v_lshlrev_b64 v[180:181], 12, v[180:181]
	v_lshl_add_u64 v[180:181], v[178:179], 0, v[180:181]
	v_lshl_add_u64 v[180:181], v[176:177], 2, v[180:181]
	global_load_dwordx4 v[132:135], v[180:181], off
	global_load_dwordx4 v[136:139], v[180:181], off offset:16
	global_load_dwordx4 v[140:143], v[180:181], off offset:512
	global_load_dwordx4 v[144:147], v[180:181], off offset:528
	s_waitcnt vmcnt(4)
	v_pk_add_f32 v[32:33], v[32:33], v[148:149]
	v_pk_add_f32 v[34:35], v[34:35], v[150:151]
	v_pk_add_f32 v[28:29], v[28:29], v[152:153]
	v_pk_add_f32 v[30:31], v[30:31], v[154:155]
	v_pk_add_f32 v[24:25], v[24:25], v[156:157]
	v_pk_add_f32 v[26:27], v[26:27], v[158:159]
	v_pk_add_f32 v[20:21], v[20:21], v[160:161]
	v_pk_add_f32 v[22:23], v[22:23], v[162:163]
	s_waitcnt vmcnt(0)
	v_pk_add_f32 v[14:15], v[14:15], v[132:133]
	v_pk_add_f32 v[16:17], v[16:17], v[134:135]
	v_pk_add_f32 v[10:11], v[10:11], v[136:137]
	v_pk_add_f32 v[12:13], v[12:13], v[138:139]
	v_pk_add_f32 v[6:7], v[6:7], v[140:141]
	v_pk_add_f32 v[8:9], v[8:9], v[142:143]
	v_pk_add_f32 v[2:3], v[2:3], v[144:145]
	v_pk_add_f32 v[4:5], v[4:5], v[146:147]
	v_cmp_lt_i32_e32 vcc, s23, v185
	v_add_u32_e32 v18, 0xffff8000, v185
	v_mov_b32_e32 v180, s12
	v_mov_b32_e32 v181, s13
	v_mov_b32_e32 v178, s14
	v_mov_b32_e32 v179, s15
	v_cndmask_b32_e32 v18, v185, v18, vcc
	v_cndmask_b32_e32 v180, v180, v178, vcc
	v_cndmask_b32_e32 v181, v181, v179, vcc
	v_lshlrev_b64 v[226:227], 12, v[18:19]
	v_lshl_add_u64 v[226:227], v[180:181], 0, v[226:227]
	v_lshl_add_u64 v[226:227], v[176:177], 2, v[226:227]
	v_mov_b32_e32 v18, v185
	v_lshlrev_b64 v[228:229], 11, v[18:19]
	v_lshl_add_u64 v[228:229], s[16:17], 0, v[228:229]
	v_lshl_add_u64 v[228:229], v[176:177], 1, v[228:229]
	v_lshlrev_b64 v[230:231], 6, v[18:19]
	v_lshl_add_u64 v[230:231], s[18:19], 0, v[230:231]
	v_lshl_add_u64 v[230:231], s[30:31], 2, v[230:231]
	v_lshl_add_u64 v[230:231], v[230:231], 0, s[48:49]
	v_mov_b32_e32 v232, v226
	v_mov_b32_e32 v233, v227
	global_store_dwordx4 v[232:233], v[128:131], off
	global_store_dwordx4 v[232:233], v[124:127], off offset:16
	global_store_dwordx4 v[232:233], v[120:123], off offset:512
	global_store_dwordx4 v[232:233], v[116:119], off offset:528
	s_and_b64 vcc, exec, s[34:35]
	s_cbranch_vccz .Lop_nofeed0
	v_mov_b32_e32 v234, v228
	v_mov_b32_e32 v235, v229
	v_cvt_pk_bf16_f32 v132, v128, v129
	v_cvt_pk_bf16_f32 v133, v130, v131
	v_cvt_pk_bf16_f32 v134, v124, v125
	v_cvt_pk_bf16_f32 v135, v126, v127
	v_cvt_pk_bf16_f32 v136, v120, v121
	v_cvt_pk_bf16_f32 v137, v122, v123
	v_cvt_pk_bf16_f32 v138, v116, v117
	v_cvt_pk_bf16_f32 v139, v118, v119
	global_store_dwordx4 v[234:235], v[132:135], off
	global_store_dwordx4 v[234:235], v[136:139], off offset:256
	v_mul_f32_e32 v148, v129, v129
	v_mul_f32_e32 v18, v131, v131
	v_fmac_f32_e32 v148, v128, v128
	v_fmac_f32_e32 v18, v130, v130
	v_add_f32_e32 v148, v148, v18
	v_mul_f32_e32 v149, v125, v125
	v_mul_f32_e32 v18, v127, v127
	v_fmac_f32_e32 v149, v124, v124
	v_fmac_f32_e32 v18, v126, v126
	v_add_f32_e32 v149, v149, v18
	v_mul_f32_e32 v150, v121, v121
	v_mul_f32_e32 v18, v123, v123
	v_fmac_f32_e32 v150, v120, v120
	v_fmac_f32_e32 v18, v122, v122
	v_add_f32_e32 v150, v150, v18
	v_mul_f32_e32 v151, v117, v117
	v_mul_f32_e32 v18, v119, v119
	v_fmac_f32_e32 v151, v116, v116
	v_fmac_f32_e32 v18, v118, v118
	v_add_f32_e32 v151, v151, v18
	v_add_f32_e32 v148, v148, v149
	v_add_f32_e32 v150, v150, v151
	v_add_f32_e32 v18, v148, v150
	v_mov_b32_e32 v180, v18
	s_nop 1
	v_permlane16_swap_b32_e32 v18, v180
	v_add_f32_e32 v18, v18, v180
	v_mov_b32_e32 v180, v18
	s_nop 1
	v_permlane32_swap_b32_e32 v18, v180
	v_mov_b32_e32 v236, v230
	v_mov_b32_e32 v237, v231
	v_add_f32_e32 v18, v18, v180
	s_and_saveexec_b64 s[6:7], s[4:5]
	global_store_dword v[236:237], v18, off
	s_or_b64 exec, exec, s[6:7]
; __device__ __forceinline__ u32x4 pack8(const f32x4& v0, const f32x4& v1) { u32x4 w; w.x = cvt_pk_bf16(v0[0], v0[1]); w.y = cvt_pk_bf16(v0[2], v0[3]); w.z = cvt_pk_bf16(v1[0], v1[1]); w.w = cvt_pk_bf16(v1[2], v1[3]); return w; }
; __device__ __forceinline__ float sumsq8(const f32x4& a, const f32x4& b) { return (a[0] * a[0] + a[1] * a[1]) + (a[2] * a[2] + a[3] * a[3]) + (b[0] * b[0] + b[1] * b[1]) + (b[2] * b[2] + b[3] * b[3]); }
;     __device__ __forceinline__ void operator()(const f32x4 (&acc)[2][2][4][2], const Unit& u, int wr, int wc, int fr, int fq) const {
;     ...
;                 int row_ = row0 + ai * 128 + m * 16; asm volatile("" : "+v"(row_)); const int row = row_;
;                 f32x4 cu[4] = {nx[0], nx[1], nx[2], nx[3]};
;                 if (ai * 4 + m < 7) { const int it = ai * 4 + m + 1; int r_ = row0 + (it >> 2) * 128 + (it & 3) * 16; asm volatile("" : "+v"(r_)); const float* rs = rsrc(r_) + col0;
;                     nx[0] = *(const f32x4*)(rs); nx[1] = *(const f32x4*)(rs + 4); nx[2] = *(const f32x4*)(rs + 128); nx[3] = *(const f32x4*)(rs + 132); }
;                 float* rd = row < MR ? out_real + (size_t)row * 1024 : XM + (size_t)(row - MR) * 1024;
;                 float s = 0.f;
; #pragma unroll
;                 for (int bj = 0; bj < 2; ++bj) {
;                     const int col = col0 + bj * 128;
;                     const f32x4 x0 = cu[2 * bj] + acc[ai][bj][m][0], x1 = cu[2 * bj + 1] + acc[ai][bj][m][1];
;                     *(f32x4*)(rd + col) = x0; *(f32x4*)(rd + col + 4) = x1;
;                     if (feed_next) { *(u32x4*)(XB + (size_t)row * 1024 + col) = pack8(x0, x1); s += sumsq8(x0, x1); }
;                 }
;                 if (feed_next) { s = quad_sum(s); if (fq == 0) SSQX[(size_t)row * 16 + u.pn * 4 + wc] = s; }
;                 asm volatile("" ::: "memory");
.Lop_nofeed0:
	v_add_co_u32_e32 v232, vcc, 0x10000, v226
	s_nop 1
	v_addc_co_u32_e32 v233, vcc, 0, v227, vcc
	global_store_dwordx4 v[232:233], v[112:115], off
	global_store_dwordx4 v[232:233], v[108:111], off offset:16
	global_store_dwordx4 v[232:233], v[104:107], off offset:512
	global_store_dwordx4 v[232:233], v[100:103], off offset:528
	s_and_b64 vcc, exec, s[34:35]
	s_cbranch_vccz .Lop_nofeed1
	v_add_co_u32_e32 v234, vcc, 0x8000, v228
	s_nop 1
	v_addc_co_u32_e32 v235, vcc, 0, v229, vcc
	v_cvt_pk_bf16_f32 v140, v112, v113
	v_cvt_pk_bf16_f32 v141, v114, v115
	v_cvt_pk_bf16_f32 v142, v108, v109
	v_cvt_pk_bf16_f32 v143, v110, v111
	v_cvt_pk_bf16_f32 v144, v104, v105
	v_cvt_pk_bf16_f32 v145, v106, v107
	v_cvt_pk_bf16_f32 v146, v100, v101
	v_cvt_pk_bf16_f32 v147, v102, v103
	global_store_dwordx4 v[234:235], v[140:143], off
	global_store_dwordx4 v[234:235], v[144:147], off offset:256
	v_mul_f32_e32 v148, v113, v113
	v_mul_f32_e32 v18, v115, v115
	v_fmac_f32_e32 v148, v112, v112
	v_fmac_f32_e32 v18, v114, v114
	v_add_f32_e32 v148, v148, v18
	v_mul_f32_e32 v149, v109, v109
	v_mul_f32_e32 v18, v111, v111
	v_fmac_f32_e32 v149, v108, v108
	v_fmac_f32_e32 v18, v110, v110
	v_add_f32_e32 v149, v149, v18
	v_mul_f32_e32 v150, v105, v105
	v_mul_f32_e32 v18, v107, v107
	v_fmac_f32_e32 v150, v104, v104
	v_fmac_f32_e32 v18, v106, v106
	v_add_f32_e32 v150, v150, v18
	v_mul_f32_e32 v151, v101, v101
	v_mul_f32_e32 v18, v103, v103
	v_fmac_f32_e32 v151, v100, v100
	v_fmac_f32_e32 v18, v102, v102
	v_add_f32_e32 v151, v151, v18
	v_add_f32_e32 v148, v148, v149
	v_add_f32_e32 v150, v150, v151
	v_add_f32_e32 v18, v148, v150
	v_mov_b32_e32 v180, v18
	s_nop 1
	v_permlane16_swap_b32_e32 v18, v180
	v_add_f32_e32 v18, v18, v180
	v_mov_b32_e32 v180, v18
	s_nop 1
	v_permlane32_swap_b32_e32 v18, v180
	v_add_co_u32_e32 v236, vcc, 0x400, v230
	s_nop 1
	v_addc_co_u32_e32 v237, vcc, 0, v231, vcc
	v_add_f32_e32 v18, v18, v180
	s_and_saveexec_b64 s[6:7], s[4:5]
	global_store_dword v[236:237], v18, off
	s_or_b64 exec, exec, s[6:7]
.Lop_nofeed1:
	v_add_co_u32_e32 v232, vcc, 0x20000, v226
	s_nop 1
	v_addc_co_u32_e32 v233, vcc, 0, v227, vcc
	global_store_dwordx4 v[232:233], v[96:99], off
	global_store_dwordx4 v[232:233], v[92:95], off offset:16
	global_store_dwordx4 v[232:233], v[88:91], off offset:512
	global_store_dwordx4 v[232:233], v[84:87], off offset:528
	s_and_b64 vcc, exec, s[34:35]
	s_cbranch_vccz .Lop_nofeed2
	v_add_co_u32_e32 v234, vcc, 0x10000, v228
	s_nop 1
	v_addc_co_u32_e32 v235, vcc, 0, v229, vcc
	v_cvt_pk_bf16_f32 v132, v96, v97
	v_cvt_pk_bf16_f32 v133, v98, v99
	v_cvt_pk_bf16_f32 v134, v92, v93
	v_cvt_pk_bf16_f32 v135, v94, v95
	v_cvt_pk_bf16_f32 v136, v88, v89
	v_cvt_pk_bf16_f32 v137, v90, v91
	v_cvt_pk_bf16_f32 v138, v84, v85
	v_cvt_pk_bf16_f32 v139, v86, v87
	global_store_dwordx4 v[234:235], v[132:135], off
	global_store_dwordx4 v[234:235], v[136:139], off offset:256
	v_mul_f32_e32 v148, v97, v97
	v_mul_f32_e32 v18, v99, v99
	v_fmac_f32_e32 v148, v96, v96
	v_fmac_f32_e32 v18, v98, v98
	v_add_f32_e32 v148, v148, v18
	v_mul_f32_e32 v149, v93, v93
	v_mul_f32_e32 v18, v95, v95
	v_fmac_f32_e32 v149, v92, v92
	v_fmac_f32_e32 v18, v94, v94
	v_add_f32_e32 v149, v149, v18
	v_mul_f32_e32 v150, v89, v89
	v_mul_f32_e32 v18, v91, v91
	v_fmac_f32_e32 v150, v88, v88
	v_fmac_f32_e32 v18, v90, v90
	v_add_f32_e32 v150, v150, v18
	v_mul_f32_e32 v151, v85, v85
	v_mul_f32_e32 v18, v87, v87
	v_fmac_f32_e32 v151, v84, v84
	v_fmac_f32_e32 v18, v86, v86
	v_add_f32_e32 v151, v151, v18
	v_add_f32_e32 v148, v148, v149
	v_add_f32_e32 v150, v150, v151
	v_add_f32_e32 v18, v148, v150
	v_mov_b32_e32 v180, v18
	s_nop 1
	v_permlane16_swap_b32_e32 v18, v180
	v_add_f32_e32 v18, v18, v180
	v_mov_b32_e32 v180, v18
	s_nop 1
	v_permlane32_swap_b32_e32 v18, v180
	v_add_co_u32_e32 v236, vcc, 0x800, v230
	s_nop 1
	v_addc_co_u32_e32 v237, vcc, 0, v231, vcc
	v_add_f32_e32 v18, v18, v180
	s_and_saveexec_b64 s[6:7], s[4:5]
	global_store_dword v[236:237], v18, off
	s_or_b64 exec, exec, s[6:7]
.Lop_nofeed2:
	v_add_co_u32_e32 v232, vcc, 0x30000, v226
	s_nop 1
	v_addc_co_u32_e32 v233, vcc, 0, v227, vcc
	global_store_dwordx4 v[232:233], v[80:83], off
	global_store_dwordx4 v[232:233], v[76:79], off offset:16
	global_store_dwordx4 v[232:233], v[72:75], off offset:512
	global_store_dwordx4 v[232:233], v[68:71], off offset:528
	s_and_b64 vcc, exec, s[34:35]
	s_cbranch_vccz .Lop_nofeed3
	v_add_co_u32_e32 v234, vcc, 0x18000, v228
	s_nop 1
	v_addc_co_u32_e32 v235, vcc, 0, v229, vcc
	v_cvt_pk_bf16_f32 v140, v80, v81
	v_cvt_pk_bf16_f32 v141, v82, v83
	v_cvt_pk_bf16_f32 v142, v76, v77
	v_cvt_pk_bf16_f32 v143, v78, v79
	v_cvt_pk_bf16_f32 v144, v72, v73
	v_cvt_pk_bf16_f32 v145, v74, v75
	v_cvt_pk_bf16_f32 v146, v68, v69
	v_cvt_pk_bf16_f32 v147, v70, v71
	global_store_dwordx4 v[234:235], v[140:143], off
	global_store_dwordx4 v[234:235], v[144:147], off offset:256
	v_mul_f32_e32 v148, v81, v81
	v_mul_f32_e32 v18, v83, v83
	v_fmac_f32_e32 v148, v80, v80
	v_fmac_f32_e32 v18, v82, v82
	v_add_f32_e32 v148, v148, v18
	v_mul_f32_e32 v149, v77, v77
	v_mul_f32_e32 v18, v79, v79
	v_fmac_f32_e32 v149, v76, v76
	v_fmac_f32_e32 v18, v78, v78
	v_add_f32_e32 v149, v149, v18
	v_mul_f32_e32 v150, v73, v73
	v_mul_f32_e32 v18, v75, v75
	v_fmac_f32_e32 v150, v72, v72
	v_fmac_f32_e32 v18, v74, v74
	v_add_f32_e32 v150, v150, v18
	v_mul_f32_e32 v151, v69, v69
	v_mul_f32_e32 v18, v71, v71
	v_fmac_f32_e32 v151, v68, v68
	v_fmac_f32_e32 v18, v70, v70
	v_add_f32_e32 v151, v151, v18
	v_add_f32_e32 v148, v148, v149
	v_add_f32_e32 v150, v150, v151
	v_add_f32_e32 v18, v148, v150
	v_mov_b32_e32 v180, v18
	s_nop 1
	v_permlane16_swap_b32_e32 v18, v180
	v_add_f32_e32 v18, v18, v180
	v_mov_b32_e32 v180, v18
	s_nop 1
	v_permlane32_swap_b32_e32 v18, v180
	v_add_co_u32_e32 v236, vcc, 0xc00, v230
	s_nop 1
	v_addc_co_u32_e32 v237, vcc, 0, v231, vcc
	v_add_f32_e32 v18, v18, v180
	s_and_saveexec_b64 s[6:7], s[4:5]
	global_store_dword v[236:237], v18, off
	s_or_b64 exec, exec, s[6:7]
; __device__ __forceinline__ u32x4 pack8(const f32x4& v0, const f32x4& v1) { u32x4 w; w.x = cvt_pk_bf16(v0[0], v0[1]); w.y = cvt_pk_bf16(v0[2], v0[3]); w.z = cvt_pk_bf16(v1[0], v1[1]); w.w = cvt_pk_bf16(v1[2], v1[3]); return w; }
; __device__ __forceinline__ float sumsq8(const f32x4& a, const f32x4& b) { return (a[0] * a[0] + a[1] * a[1]) + (a[2] * a[2] + a[3] * a[3]) + (b[0] * b[0] + b[1] * b[1]) + (b[2] * b[2] + b[3] * b[3]); }
;     __device__ __forceinline__ void operator()(const f32x4 (&acc)[2][2][4][2], const Unit& u, int wr, int wc, int fr, int fq) const {
;     ...
;                 int row_ = row0 + ai * 128 + m * 16; asm volatile("" : "+v"(row_)); const int row = row_;
;                 f32x4 cu[4] = {nx[0], nx[1], nx[2], nx[3]};
;                 if (ai * 4 + m < 7) { const int it = ai * 4 + m + 1; int r_ = row0 + (it >> 2) * 128 + (it & 3) * 16; asm volatile("" : "+v"(r_)); const float* rs = rsrc(r_) + col0;
;                     nx[0] = *(const f32x4*)(rs); nx[1] = *(const f32x4*)(rs + 4); nx[2] = *(const f32x4*)(rs + 128); nx[3] = *(const f32x4*)(rs + 132); }
;                 float* rd = row < MR ? out_real + (size_t)row * 1024 : XM + (size_t)(row - MR) * 1024;
;                 float s = 0.f;
; #pragma unroll
;                 for (int bj = 0; bj < 2; ++bj) {
;                     const int col = col0 + bj * 128;
;                     const f32x4 x0 = cu[2 * bj] + acc[ai][bj][m][0], x1 = cu[2 * bj + 1] + acc[ai][bj][m][1];
;                     *(f32x4*)(rd + col) = x0; *(f32x4*)(rd + col + 4) = x1;
;                     if (feed_next) { *(u32x4*)(XB + (size_t)row * 1024 + col) = pack8(x0, x1); s += sumsq8(x0, x1); }
;                 }
;                 if (feed_next) { s = quad_sum(s); if (fq == 0) SSQX[(size_t)row * 16 + u.pn * 4 + wc] = s; }
;                 asm volatile("" ::: "memory");
.Lop_nofeed3:
	v_add_co_u32_e32 v232, vcc, 0x80000, v226
	s_nop 1
	v_addc_co_u32_e32 v233, vcc, 0, v227, vcc
	global_store_dwordx4 v[232:233], v[64:67], off
	global_store_dwordx4 v[232:233], v[60:63], off offset:16
	global_store_dwordx4 v[232:233], v[56:59], off offset:512
	global_store_dwordx4 v[232:233], v[52:55], off offset:528
	s_and_b64 vcc, exec, s[34:35]
	s_cbranch_vccz .Lop_nofeed4
	v_add_co_u32_e32 v234, vcc, 0x40000, v228
	s_nop 1
	v_addc_co_u32_e32 v235, vcc, 0, v229, vcc
	v_cvt_pk_bf16_f32 v132, v64, v65
	v_cvt_pk_bf16_f32 v133, v66, v67
	v_cvt_pk_bf16_f32 v134, v60, v61
	v_cvt_pk_bf16_f32 v135, v62, v63
	v_cvt_pk_bf16_f32 v136, v56, v57
	v_cvt_pk_bf16_f32 v137, v58, v59
	v_cvt_pk_bf16_f32 v138, v52, v53
	v_cvt_pk_bf16_f32 v139, v54, v55
	global_store_dwordx4 v[234:235], v[132:135], off
	global_store_dwordx4 v[234:235], v[136:139], off offset:256
	v_mul_f32_e32 v148, v65, v65
	v_mul_f32_e32 v18, v67, v67
	v_fmac_f32_e32 v148, v64, v64
	v_fmac_f32_e32 v18, v66, v66
	v_add_f32_e32 v148, v148, v18
	v_mul_f32_e32 v149, v61, v61
	v_mul_f32_e32 v18, v63, v63
	v_fmac_f32_e32 v149, v60, v60
	v_fmac_f32_e32 v18, v62, v62
	v_add_f32_e32 v149, v149, v18
	v_mul_f32_e32 v150, v57, v57
	v_mul_f32_e32 v18, v59, v59
	v_fmac_f32_e32 v150, v56, v56
	v_fmac_f32_e32 v18, v58, v58
	v_add_f32_e32 v150, v150, v18
	v_mul_f32_e32 v151, v53, v53
	v_mul_f32_e32 v18, v55, v55
	v_fmac_f32_e32 v151, v52, v52
	v_fmac_f32_e32 v18, v54, v54
	v_add_f32_e32 v151, v151, v18
	v_add_f32_e32 v148, v148, v149
	v_add_f32_e32 v150, v150, v151
	v_add_f32_e32 v18, v148, v150
	v_mov_b32_e32 v180, v18
	s_nop 1
	v_permlane16_swap_b32_e32 v18, v180
	v_add_f32_e32 v18, v18, v180
	v_mov_b32_e32 v180, v18
	s_nop 1
	v_permlane32_swap_b32_e32 v18, v180
	v_add_co_u32_e32 v236, vcc, 0x2000, v230
	s_nop 1
	v_addc_co_u32_e32 v237, vcc, 0, v231, vcc
	v_add_f32_e32 v18, v18, v180
	s_and_saveexec_b64 s[6:7], s[4:5]
	global_store_dword v[236:237], v18, off
	s_or_b64 exec, exec, s[6:7]
.Lop_nofeed4:
	v_add_co_u32_e32 v232, vcc, 0x90000, v226
	s_nop 1
	v_addc_co_u32_e32 v233, vcc, 0, v227, vcc
	global_store_dwordx4 v[232:233], v[48:51], off
	global_store_dwordx4 v[232:233], v[44:47], off offset:16
	global_store_dwordx4 v[232:233], v[40:43], off offset:512
	global_store_dwordx4 v[232:233], v[36:39], off offset:528
	s_and_b64 vcc, exec, s[34:35]
	s_cbranch_vccz .Lop_nofeed5
	v_add_co_u32_e32 v234, vcc, 0x48000, v228
	s_nop 1
	v_addc_co_u32_e32 v235, vcc, 0, v229, vcc
	v_cvt_pk_bf16_f32 v140, v48, v49
	v_cvt_pk_bf16_f32 v141, v50, v51
	v_cvt_pk_bf16_f32 v142, v44, v45
	v_cvt_pk_bf16_f32 v143, v46, v47
	v_cvt_pk_bf16_f32 v144, v40, v41
	v_cvt_pk_bf16_f32 v145, v42, v43
	v_cvt_pk_bf16_f32 v146, v36, v37
	v_cvt_pk_bf16_f32 v147, v38, v39
	global_store_dwordx4 v[234:235], v[140:143], off
	global_store_dwordx4 v[234:235], v[144:147], off offset:256
	v_mul_f32_e32 v148, v49, v49
	v_mul_f32_e32 v18, v51, v51
	v_fmac_f32_e32 v148, v48, v48
	v_fmac_f32_e32 v18, v50, v50
	v_add_f32_e32 v148, v148, v18
	v_mul_f32_e32 v149, v45, v45
	v_mul_f32_e32 v18, v47, v47
	v_fmac_f32_e32 v149, v44, v44
	v_fmac_f32_e32 v18, v46, v46
	v_add_f32_e32 v149, v149, v18
	v_mul_f32_e32 v150, v41, v41
	v_mul_f32_e32 v18, v43, v43
	v_fmac_f32_e32 v150, v40, v40
	v_fmac_f32_e32 v18, v42, v42
	v_add_f32_e32 v150, v150, v18
	v_mul_f32_e32 v151, v37, v37
	v_mul_f32_e32 v18, v39, v39
	v_fmac_f32_e32 v151, v36, v36
	v_fmac_f32_e32 v18, v38, v38
	v_add_f32_e32 v151, v151, v18
	v_add_f32_e32 v148, v148, v149
	v_add_f32_e32 v150, v150, v151
	v_add_f32_e32 v18, v148, v150
	v_mov_b32_e32 v180, v18
	s_nop 1
	v_permlane16_swap_b32_e32 v18, v180
	v_add_f32_e32 v18, v18, v180
	v_mov_b32_e32 v180, v18
	s_nop 1
	v_permlane32_swap_b32_e32 v18, v180
	v_add_co_u32_e32 v236, vcc, 0x2400, v230
	s_nop 1
	v_addc_co_u32_e32 v237, vcc, 0, v231, vcc
	v_add_f32_e32 v18, v18, v180
	s_and_saveexec_b64 s[6:7], s[4:5]
	global_store_dword v[236:237], v18, off
	s_or_b64 exec, exec, s[6:7]
; __device__ __forceinline__ int lane_id_v() { int l; asm volatile("v_mbcnt_lo_u32_b32 %0, -1, 0\n\tv_mbcnt_hi_u32_b32 %0, -1, %0" : "=v"(l)); return l; }
; #define PG8_BAR __builtin_amdgcn_s_barrier()
; template <class Epi, class Sched, bool HALFN = false>
; __device__ __forceinline__ void gemm_phase(LAS unsigned char* lds, const Gemm g, const Sched& S, const Epi& E, int wave_s) {
;     ...
;         if (!has_next) break;
; #pragma unroll
;         for (int a = 0; a < 2; ++a)
; #pragma unroll
;             for (int b = 0; b < 2; ++b)
; #pragma unroll
;                 for (int m = 0; m < 4; ++m)
; #pragma unroll
;                     for (int n = 0; n < 2; ++n) acc[a][b][m][n] = (f32x4){0.f, 0.f, 0.f, 0.f};
;         cur = nxt; cA = nA; cB = nB; ++ui;
;         if constexpr (Epi::PREFETCH) E.prefetch(cur, wid, lane_id_v());
;         if constexpr (HALFN) E.gates(cur, wr, wc, lane_id_v(), gpre);
;         if (wr == 1) PG8_BAR;
;     __device__ __forceinline__ void operator()(const f32x4 (&acc)[2][2][4][2], const Unit& u, int wr, int wc, int fr, int fq) const {
;     ...
;                 int row_ = row0 + ai * 128 + m * 16; asm volatile("" : "+v"(row_)); const int row = row_;
;                 f32x4 cu[4] = {nx[0], nx[1], nx[2], nx[3]};
;                 if (ai * 4 + m < 7) { const int it = ai * 4 + m + 1; int r_ = row0 + (it >> 2) * 128 + (it & 3) * 16; asm volatile("" : "+v"(r_)); const float* rs = rsrc(r_) + col0;
;                     nx[0] = *(const f32x4*)(rs); nx[1] = *(const f32x4*)(rs + 4); nx[2] = *(const f32x4*)(rs + 128); nx[3] = *(const f32x4*)(rs + 132); }
;                 float* rd = row < MR ? out_real + (size_t)row * 1024 : XM + (size_t)(row - MR) * 1024;
;                 float s = 0.f;
; #pragma unroll
;                 for (int bj = 0; bj < 2; ++bj) {
;                     const int col = col0 + bj * 128;
;                     const f32x4 x0 = cu[2 * bj] + acc[ai][bj][m][0], x1 = cu[2 * bj + 1] + acc[ai][bj][m][1];
;                     *(f32x4*)(rd + col) = x0; *(f32x4*)(rd + col + 4) = x1;
;                     if (feed_next) { *(u32x4*)(XB + (size_t)row * 1024 + col) = pack8(x0, x1); s += sumsq8(x0, x1); }
;                 }
;                 if (feed_next) { s = quad_sum(s); if (fq == 0) SSQX[(size_t)row * 16 + u.pn * 4 + wc] = s; }
;                 asm volatile("" ::: "memory");
.Lop_nofeed5:
	v_add_co_u32_e32 v232, vcc, 0xa0000, v226
	s_nop 1
	v_addc_co_u32_e32 v233, vcc, 0, v227, vcc
	global_store_dwordx4 v[232:233], v[32:35], off
	global_store_dwordx4 v[232:233], v[28:31], off offset:16
	global_store_dwordx4 v[232:233], v[24:27], off offset:512
	global_store_dwordx4 v[232:233], v[20:23], off offset:528
	s_and_b64 vcc, exec, s[34:35]
	s_cbranch_vccz .Lop_nofeed6
	v_add_co_u32_e32 v234, vcc, 0x50000, v228
	s_nop 1
	v_addc_co_u32_e32 v235, vcc, 0, v229, vcc
	v_cvt_pk_bf16_f32 v132, v32, v33
	v_cvt_pk_bf16_f32 v133, v34, v35
	v_cvt_pk_bf16_f32 v134, v28, v29
	v_cvt_pk_bf16_f32 v135, v30, v31
	v_cvt_pk_bf16_f32 v136, v24, v25
	v_cvt_pk_bf16_f32 v137, v26, v27
	v_cvt_pk_bf16_f32 v138, v20, v21
	v_cvt_pk_bf16_f32 v139, v22, v23
	global_store_dwordx4 v[234:235], v[132:135], off
	global_store_dwordx4 v[234:235], v[136:139], off offset:256
	v_mul_f32_e32 v148, v33, v33
	v_mul_f32_e32 v18, v35, v35
	v_fmac_f32_e32 v148, v32, v32
	v_fmac_f32_e32 v18, v34, v34
	v_add_f32_e32 v148, v148, v18
	v_mul_f32_e32 v149, v29, v29
	v_mul_f32_e32 v18, v31, v31
	v_fmac_f32_e32 v149, v28, v28
	v_fmac_f32_e32 v18, v30, v30
	v_add_f32_e32 v149, v149, v18
	v_mul_f32_e32 v150, v25, v25
	v_mul_f32_e32 v18, v27, v27
	v_fmac_f32_e32 v150, v24, v24
	v_fmac_f32_e32 v18, v26, v26
	v_add_f32_e32 v150, v150, v18
	v_mul_f32_e32 v151, v21, v21
	v_mul_f32_e32 v18, v23, v23
	v_fmac_f32_e32 v151, v20, v20
	v_fmac_f32_e32 v18, v22, v22
	v_add_f32_e32 v151, v151, v18
	v_add_f32_e32 v148, v148, v149
	v_add_f32_e32 v150, v150, v151
	v_add_f32_e32 v18, v148, v150
	v_mov_b32_e32 v180, v18
	s_nop 1
	v_permlane16_swap_b32_e32 v18, v180
	v_add_f32_e32 v18, v18, v180
	v_mov_b32_e32 v180, v18
	s_nop 1
	v_permlane32_swap_b32_e32 v18, v180
	v_add_co_u32_e32 v236, vcc, 0x2800, v230
	s_nop 1
	v_addc_co_u32_e32 v237, vcc, 0, v231, vcc
	v_add_f32_e32 v18, v18, v180
	s_and_saveexec_b64 s[6:7], s[4:5]
	global_store_dword v[236:237], v18, off
	s_or_b64 exec, exec, s[6:7]
.Lop_nofeed6:
	v_add_co_u32_e32 v232, vcc, 0xb0000, v226
	s_nop 1
	v_addc_co_u32_e32 v233, vcc, 0, v227, vcc
	global_store_dwordx4 v[232:233], v[14:17], off
	global_store_dwordx4 v[232:233], v[10:13], off offset:16
	global_store_dwordx4 v[232:233], v[6:9], off offset:512
	global_store_dwordx4 v[232:233], v[2:5], off offset:528
	s_and_b64 vcc, exec, s[34:35]
	s_cbranch_vccz .Lop_nofeed7
	v_add_co_u32_e32 v234, vcc, 0x58000, v228
	s_nop 1
	v_addc_co_u32_e32 v235, vcc, 0, v229, vcc
	v_cvt_pk_bf16_f32 v140, v14, v15
	v_cvt_pk_bf16_f32 v141, v16, v17
	v_cvt_pk_bf16_f32 v142, v10, v11
	v_cvt_pk_bf16_f32 v143, v12, v13
	v_cvt_pk_bf16_f32 v144, v6, v7
	v_cvt_pk_bf16_f32 v145, v8, v9
	v_cvt_pk_bf16_f32 v146, v2, v3
	v_cvt_pk_bf16_f32 v147, v4, v5
	global_store_dwordx4 v[234:235], v[140:143], off
	global_store_dwordx4 v[234:235], v[144:147], off offset:256
	v_mul_f32_e32 v148, v15, v15
	v_mul_f32_e32 v18, v17, v17
	v_fmac_f32_e32 v148, v14, v14
	v_fmac_f32_e32 v18, v16, v16
	v_add_f32_e32 v148, v148, v18
	v_mul_f32_e32 v149, v11, v11
	v_mul_f32_e32 v18, v13, v13
	v_fmac_f32_e32 v149, v10, v10
	v_fmac_f32_e32 v18, v12, v12
	v_add_f32_e32 v149, v149, v18
	v_mul_f32_e32 v150, v7, v7
	v_mul_f32_e32 v18, v9, v9
	v_fmac_f32_e32 v150, v6, v6
	v_fmac_f32_e32 v18, v8, v8
	v_add_f32_e32 v150, v150, v18
	v_mul_f32_e32 v151, v3, v3
	v_mul_f32_e32 v18, v5, v5
	v_fmac_f32_e32 v151, v2, v2
	v_fmac_f32_e32 v18, v4, v4
	v_add_f32_e32 v151, v151, v18
	v_add_f32_e32 v148, v148, v149
	v_add_f32_e32 v150, v150, v151
	v_add_f32_e32 v18, v148, v150
	v_mov_b32_e32 v180, v18
	s_nop 1
	v_permlane16_swap_b32_e32 v18, v180
	v_add_f32_e32 v18, v18, v180
	v_mov_b32_e32 v180, v18
	s_nop 1
	v_permlane32_swap_b32_e32 v18, v180
	v_add_co_u32_e32 v236, vcc, 0x2c00, v230
	s_nop 1
	v_addc_co_u32_e32 v237, vcc, 0, v231, vcc
	v_add_f32_e32 v18, v18, v180
	s_and_saveexec_b64 s[6:7], s[4:5]
	global_store_dword v[236:237], v18, off
	s_or_b64 exec, exec, s[6:7]
.Lop_nofeed7:
	s_branch .LBB0_1068
.LBB0_1068:
	s_andn2_b64 vcc, exec, s[8:9]
	s_mov_b64 s[4:5], -1
	s_cbranch_vccnz .LBB0_977
	s_andn2_b64 vcc, exec, s[10:11]
	s_cbranch_vccnz .LBB0_976
	s_barrier
	s_branch .LBB0_976
